# P11 EpiRes main epilogue hand-rewritten: 4 rows of x_old loads in flight, counted vmcnt waits, batched bpermute reductions
# baseline (speedup 1.0000x reference)
.LBB0_3134:
	s_lshl_b32 s23, s42, 8
	s_add_i32 s23, s23, s53
	v_or_b32_e32 v236, s23, v164
	v_ashrrev_i32_e32 v237, 31, v236
	v_lshl_or_b32 v156, s10, 8, v171
	v_ashrrev_i32_e32 v157, 31, v156
	v_add_u32_e32 v158, 0xffffbc00, v236
	v_cmp_gt_i32_e32 vcc, s66, v236
	v_mov_b32_e32 v160, s59
	v_mov_b32_e32 v161, s27
	v_cndmask_b32_e32 v159, 0, v237, vcc
	v_cndmask_b32_e32 v158, v158, v236, vcc
	v_cndmask_b32_e32 v161, v160, v161, vcc
	v_mov_b32_e32 v160, s58
	v_mov_b32_e32 v134, s26
	v_cndmask_b32_e32 v160, v160, v134, vcc
	v_lshlrev_b64 v[158:159], 12, v[158:159]
	v_lshl_add_u64 v[134:135], v[160:161], 0, v[158:159]
	v_lshl_add_u64 v[134:135], v[156:157], 2, v[134:135]
	v_lshlrev_b64 v[158:159], 11, v[236:237]
	v_lshl_add_u64 v[136:137], s[88:89], 0, v[158:159]
	v_lshl_add_u64 v[136:137], v[156:157], 1, v[136:137]
	v_lshlrev_b64 v[158:159], 6, v[236:237]
	v_lshl_add_u64 v[138:139], s[12:13], 0, v[158:159]
	s_lshl_b32 s44, s10, 4
	s_lshl_b32 s45, s52, 2
	s_add_i32 s44, s44, s45
	s_mov_b32 s45, 0
	v_lshl_add_u64 v[138:139], s[44:45], 0, v[138:139]
	global_load_dwordx4 v[176:179], v[134:135], off
	global_load_dwordx4 v[180:183], v[134:135], off offset:16
	global_load_dwordx4 v[184:187], v[134:135], off offset:512
	global_load_dwordx4 v[188:191], v[134:135], off offset:528
	s_mov_b32 s44, 0x10000
	v_lshl_add_u64 v[160:161], v[134:135], 0, s[44:45]
	global_load_dwordx4 v[192:195], v[160:161], off
	global_load_dwordx4 v[196:199], v[160:161], off offset:16
	global_load_dwordx4 v[200:203], v[160:161], off offset:512
	global_load_dwordx4 v[204:207], v[160:161], off offset:528
	s_mov_b32 s44, 0x20000
	v_lshl_add_u64 v[160:161], v[134:135], 0, s[44:45]
	global_load_dwordx4 v[208:211], v[160:161], off
	global_load_dwordx4 v[212:215], v[160:161], off offset:16
	global_load_dwordx4 v[216:219], v[160:161], off offset:512
	global_load_dwordx4 v[220:223], v[160:161], off offset:528
	s_mov_b32 s44, 0x30000
	v_lshl_add_u64 v[160:161], v[134:135], 0, s[44:45]
	global_load_dwordx4 v[224:227], v[160:161], off
	global_load_dwordx4 v[228:231], v[160:161], off offset:16
	global_load_dwordx4 v[232:235], v[160:161], off offset:512
	global_load_dwordx4 v[130:133], v[160:161], off offset:528
	s_waitcnt vmcnt(12)
	v_pk_add_f32 v[126:127], v[126:127], v[176:177]
	v_pk_add_f32 v[128:129], v[128:129], v[178:179]
	v_pk_add_f32 v[122:123], v[122:123], v[180:181]
	v_pk_add_f32 v[124:125], v[124:125], v[182:183]
	v_pk_add_f32 v[118:119], v[118:119], v[184:185]
	v_pk_add_f32 v[120:121], v[120:121], v[186:187]
	v_pk_add_f32 v[114:115], v[114:115], v[188:189]
	v_pk_add_f32 v[116:117], v[116:117], v[190:191]
	s_mov_b32 s44, 0x80000
	v_lshl_add_u64 v[160:161], v[134:135], 0, s[44:45]
	global_load_dwordx4 v[176:179], v[160:161], off
	global_load_dwordx4 v[180:183], v[160:161], off offset:16
	global_load_dwordx4 v[184:187], v[160:161], off offset:512
	global_load_dwordx4 v[188:191], v[160:161], off offset:528
	global_store_dwordx4 v[134:135], v[126:129], off
	global_store_dwordx4 v[134:135], v[122:125], off offset:16
	global_store_dwordx4 v[134:135], v[118:121], off offset:512
	global_store_dwordx4 v[134:135], v[114:117], off offset:528
	v_pk_mul_f32 v[236:237], v[126:127], v[126:127]
	v_pk_fma_f32 v[236:237], v[128:129], v[128:129], v[236:237]
	v_pk_fma_f32 v[236:237], v[122:123], v[122:123], v[236:237]
	v_pk_fma_f32 v[236:237], v[124:125], v[124:125], v[236:237]
	v_pk_fma_f32 v[236:237], v[118:119], v[118:119], v[236:237]
	v_pk_fma_f32 v[236:237], v[120:121], v[120:121], v[236:237]
	v_pk_fma_f32 v[236:237], v[114:115], v[114:115], v[236:237]
	v_pk_fma_f32 v[236:237], v[116:117], v[116:117], v[236:237]
	v_cvt_pk_bf16_f32 v126, v126, v127
	v_cvt_pk_bf16_f32 v127, v128, v129
	v_cvt_pk_bf16_f32 v128, v122, v123
	v_cvt_pk_bf16_f32 v129, v124, v125
	v_cvt_pk_bf16_f32 v118, v118, v119
	v_cvt_pk_bf16_f32 v119, v120, v121
	v_cvt_pk_bf16_f32 v120, v114, v115
	v_cvt_pk_bf16_f32 v121, v116, v117
	global_store_dwordx4 v[136:137], v[126:129], off
	global_store_dwordx4 v[136:137], v[118:121], off offset:256
	v_add_f32_e32 v122, v236, v237
	s_waitcnt vmcnt(18)
	v_pk_add_f32 v[110:111], v[110:111], v[192:193]
	v_pk_add_f32 v[112:113], v[112:113], v[194:195]
	v_pk_add_f32 v[106:107], v[106:107], v[196:197]
	v_pk_add_f32 v[108:109], v[108:109], v[198:199]
	v_pk_add_f32 v[102:103], v[102:103], v[200:201]
	v_pk_add_f32 v[104:105], v[104:105], v[202:203]
	v_pk_add_f32 v[98:99], v[98:99], v[204:205]
	v_pk_add_f32 v[100:101], v[100:101], v[206:207]
	s_mov_b32 s44, 0x90000
	v_lshl_add_u64 v[160:161], v[134:135], 0, s[44:45]
	global_load_dwordx4 v[192:195], v[160:161], off
	global_load_dwordx4 v[196:199], v[160:161], off offset:16
	global_load_dwordx4 v[200:203], v[160:161], off offset:512
	global_load_dwordx4 v[204:207], v[160:161], off offset:528
	s_mov_b32 s44, 0x10000
	v_lshl_add_u64 v[156:157], v[134:135], 0, s[44:45]
	global_store_dwordx4 v[156:157], v[110:113], off
	global_store_dwordx4 v[156:157], v[106:109], off offset:16
	global_store_dwordx4 v[156:157], v[102:105], off offset:512
	global_store_dwordx4 v[156:157], v[98:101], off offset:528
	v_pk_mul_f32 v[236:237], v[110:111], v[110:111]
	v_pk_fma_f32 v[236:237], v[112:113], v[112:113], v[236:237]
	v_pk_fma_f32 v[236:237], v[106:107], v[106:107], v[236:237]
	v_pk_fma_f32 v[236:237], v[108:109], v[108:109], v[236:237]
	v_pk_fma_f32 v[236:237], v[102:103], v[102:103], v[236:237]
	v_pk_fma_f32 v[236:237], v[104:105], v[104:105], v[236:237]
	v_pk_fma_f32 v[236:237], v[98:99], v[98:99], v[236:237]
	v_pk_fma_f32 v[236:237], v[100:101], v[100:101], v[236:237]
	v_cvt_pk_bf16_f32 v110, v110, v111
	v_cvt_pk_bf16_f32 v111, v112, v113
	v_cvt_pk_bf16_f32 v112, v106, v107
	v_cvt_pk_bf16_f32 v113, v108, v109
	v_cvt_pk_bf16_f32 v102, v102, v103
	v_cvt_pk_bf16_f32 v103, v104, v105
	v_cvt_pk_bf16_f32 v104, v98, v99
	v_cvt_pk_bf16_f32 v105, v100, v101
	s_mov_b32 s44, 0x8000
	v_lshl_add_u64 v[158:159], v[136:137], 0, s[44:45]
	global_store_dwordx4 v[158:159], v[110:113], off
	global_store_dwordx4 v[158:159], v[102:105], off offset:256
	v_add_f32_e32 v106, v236, v237
	s_waitcnt vmcnt(24)
	v_pk_add_f32 v[94:95], v[94:95], v[208:209]
	v_pk_add_f32 v[96:97], v[96:97], v[210:211]
	v_pk_add_f32 v[90:91], v[90:91], v[212:213]
	v_pk_add_f32 v[92:93], v[92:93], v[214:215]
	v_pk_add_f32 v[86:87], v[86:87], v[216:217]
	v_pk_add_f32 v[88:89], v[88:89], v[218:219]
	v_pk_add_f32 v[82:83], v[82:83], v[220:221]
	v_pk_add_f32 v[84:85], v[84:85], v[222:223]
	s_mov_b32 s44, 0xa0000
	v_lshl_add_u64 v[160:161], v[134:135], 0, s[44:45]
	global_load_dwordx4 v[208:211], v[160:161], off
	global_load_dwordx4 v[212:215], v[160:161], off offset:16
	global_load_dwordx4 v[216:219], v[160:161], off offset:512
	global_load_dwordx4 v[220:223], v[160:161], off offset:528
	s_mov_b32 s44, 0x20000
	v_lshl_add_u64 v[156:157], v[134:135], 0, s[44:45]
	global_store_dwordx4 v[156:157], v[94:97], off
	global_store_dwordx4 v[156:157], v[90:93], off offset:16
	global_store_dwordx4 v[156:157], v[86:89], off offset:512
	global_store_dwordx4 v[156:157], v[82:85], off offset:528
	v_pk_mul_f32 v[236:237], v[94:95], v[94:95]
	v_pk_fma_f32 v[236:237], v[96:97], v[96:97], v[236:237]
	v_pk_fma_f32 v[236:237], v[90:91], v[90:91], v[236:237]
	v_pk_fma_f32 v[236:237], v[92:93], v[92:93], v[236:237]
	v_pk_fma_f32 v[236:237], v[86:87], v[86:87], v[236:237]
	v_pk_fma_f32 v[236:237], v[88:89], v[88:89], v[236:237]
	v_pk_fma_f32 v[236:237], v[82:83], v[82:83], v[236:237]
	v_pk_fma_f32 v[236:237], v[84:85], v[84:85], v[236:237]
	v_cvt_pk_bf16_f32 v94, v94, v95
	v_cvt_pk_bf16_f32 v95, v96, v97
	v_cvt_pk_bf16_f32 v96, v90, v91
	v_cvt_pk_bf16_f32 v97, v92, v93
	v_cvt_pk_bf16_f32 v86, v86, v87
	v_cvt_pk_bf16_f32 v87, v88, v89
	v_cvt_pk_bf16_f32 v88, v82, v83
	v_cvt_pk_bf16_f32 v89, v84, v85
	s_mov_b32 s44, 0x10000
	v_lshl_add_u64 v[158:159], v[136:137], 0, s[44:45]
	global_store_dwordx4 v[158:159], v[94:97], off
	global_store_dwordx4 v[158:159], v[86:89], off offset:256
	v_add_f32_e32 v90, v236, v237
	s_waitcnt vmcnt(30)
	v_pk_add_f32 v[78:79], v[78:79], v[224:225]
	v_pk_add_f32 v[80:81], v[80:81], v[226:227]
	v_pk_add_f32 v[74:75], v[74:75], v[228:229]
	v_pk_add_f32 v[76:77], v[76:77], v[230:231]
	v_pk_add_f32 v[70:71], v[70:71], v[232:233]
	v_pk_add_f32 v[72:73], v[72:73], v[234:235]
	v_pk_add_f32 v[66:67], v[66:67], v[130:131]
	v_pk_add_f32 v[68:69], v[68:69], v[132:133]
	s_mov_b32 s44, 0xb0000
	v_lshl_add_u64 v[160:161], v[134:135], 0, s[44:45]
	global_load_dwordx4 v[224:227], v[160:161], off
	global_load_dwordx4 v[228:231], v[160:161], off offset:16
	global_load_dwordx4 v[232:235], v[160:161], off offset:512
	global_load_dwordx4 v[130:133], v[160:161], off offset:528
	s_mov_b32 s44, 0x30000
	v_lshl_add_u64 v[156:157], v[134:135], 0, s[44:45]
	global_store_dwordx4 v[156:157], v[78:81], off
	global_store_dwordx4 v[156:157], v[74:77], off offset:16
	global_store_dwordx4 v[156:157], v[70:73], off offset:512
	global_store_dwordx4 v[156:157], v[66:69], off offset:528
	v_pk_mul_f32 v[236:237], v[78:79], v[78:79]
	v_pk_fma_f32 v[236:237], v[80:81], v[80:81], v[236:237]
	v_pk_fma_f32 v[236:237], v[74:75], v[74:75], v[236:237]
	v_pk_fma_f32 v[236:237], v[76:77], v[76:77], v[236:237]
	v_pk_fma_f32 v[236:237], v[70:71], v[70:71], v[236:237]
	v_pk_fma_f32 v[236:237], v[72:73], v[72:73], v[236:237]
	v_pk_fma_f32 v[236:237], v[66:67], v[66:67], v[236:237]
	v_pk_fma_f32 v[236:237], v[68:69], v[68:69], v[236:237]
	v_cvt_pk_bf16_f32 v78, v78, v79
	v_cvt_pk_bf16_f32 v79, v80, v81
	v_cvt_pk_bf16_f32 v80, v74, v75
	v_cvt_pk_bf16_f32 v81, v76, v77
	v_cvt_pk_bf16_f32 v70, v70, v71
	v_cvt_pk_bf16_f32 v71, v72, v73
	v_cvt_pk_bf16_f32 v72, v66, v67
	v_cvt_pk_bf16_f32 v73, v68, v69
	s_mov_b32 s44, 0x18000
	v_lshl_add_u64 v[158:159], v[136:137], 0, s[44:45]
	global_store_dwordx4 v[158:159], v[78:81], off
	global_store_dwordx4 v[158:159], v[70:73], off offset:256
	v_add_f32_e32 v74, v236, v237
	s_waitcnt vmcnt(36)
	v_pk_add_f32 v[62:63], v[62:63], v[176:177]
	v_pk_add_f32 v[64:65], v[64:65], v[178:179]
	v_pk_add_f32 v[58:59], v[58:59], v[180:181]
	v_pk_add_f32 v[60:61], v[60:61], v[182:183]
	v_pk_add_f32 v[54:55], v[54:55], v[184:185]
	v_pk_add_f32 v[56:57], v[56:57], v[186:187]
	v_pk_add_f32 v[50:51], v[50:51], v[188:189]
	v_pk_add_f32 v[52:53], v[52:53], v[190:191]
	s_mov_b32 s44, 0x80000
	v_lshl_add_u64 v[156:157], v[134:135], 0, s[44:45]
	global_store_dwordx4 v[156:157], v[62:65], off
	global_store_dwordx4 v[156:157], v[58:61], off offset:16
	global_store_dwordx4 v[156:157], v[54:57], off offset:512
	global_store_dwordx4 v[156:157], v[50:53], off offset:528
	v_pk_mul_f32 v[236:237], v[62:63], v[62:63]
	v_pk_fma_f32 v[236:237], v[64:65], v[64:65], v[236:237]
	v_pk_fma_f32 v[236:237], v[58:59], v[58:59], v[236:237]
	v_pk_fma_f32 v[236:237], v[60:61], v[60:61], v[236:237]
	v_pk_fma_f32 v[236:237], v[54:55], v[54:55], v[236:237]
	v_pk_fma_f32 v[236:237], v[56:57], v[56:57], v[236:237]
	v_pk_fma_f32 v[236:237], v[50:51], v[50:51], v[236:237]
	v_pk_fma_f32 v[236:237], v[52:53], v[52:53], v[236:237]
	v_cvt_pk_bf16_f32 v62, v62, v63
	v_cvt_pk_bf16_f32 v63, v64, v65
	v_cvt_pk_bf16_f32 v64, v58, v59
	v_cvt_pk_bf16_f32 v65, v60, v61
	v_cvt_pk_bf16_f32 v54, v54, v55
	v_cvt_pk_bf16_f32 v55, v56, v57
	v_cvt_pk_bf16_f32 v56, v50, v51
	v_cvt_pk_bf16_f32 v57, v52, v53
	s_mov_b32 s44, 0x40000
	v_lshl_add_u64 v[158:159], v[136:137], 0, s[44:45]
	global_store_dwordx4 v[158:159], v[62:65], off
	global_store_dwordx4 v[158:159], v[54:57], off offset:256
	v_add_f32_e32 v58, v236, v237
	s_waitcnt vmcnt(32)
	v_pk_add_f32 v[46:47], v[46:47], v[192:193]
	v_pk_add_f32 v[48:49], v[48:49], v[194:195]
	v_pk_add_f32 v[42:43], v[42:43], v[196:197]
	v_pk_add_f32 v[44:45], v[44:45], v[198:199]
	v_pk_add_f32 v[38:39], v[38:39], v[200:201]
	v_pk_add_f32 v[40:41], v[40:41], v[202:203]
	v_pk_add_f32 v[34:35], v[34:35], v[204:205]
	v_pk_add_f32 v[36:37], v[36:37], v[206:207]
	s_mov_b32 s44, 0x90000
	v_lshl_add_u64 v[156:157], v[134:135], 0, s[44:45]
	global_store_dwordx4 v[156:157], v[46:49], off
	global_store_dwordx4 v[156:157], v[42:45], off offset:16
	global_store_dwordx4 v[156:157], v[38:41], off offset:512
	global_store_dwordx4 v[156:157], v[34:37], off offset:528
	v_pk_mul_f32 v[236:237], v[46:47], v[46:47]
	v_pk_fma_f32 v[236:237], v[48:49], v[48:49], v[236:237]
	v_pk_fma_f32 v[236:237], v[42:43], v[42:43], v[236:237]
	v_pk_fma_f32 v[236:237], v[44:45], v[44:45], v[236:237]
	v_pk_fma_f32 v[236:237], v[38:39], v[38:39], v[236:237]
	v_pk_fma_f32 v[236:237], v[40:41], v[40:41], v[236:237]
	v_pk_fma_f32 v[236:237], v[34:35], v[34:35], v[236:237]
	v_pk_fma_f32 v[236:237], v[36:37], v[36:37], v[236:237]
	v_cvt_pk_bf16_f32 v46, v46, v47
	v_cvt_pk_bf16_f32 v47, v48, v49
	v_cvt_pk_bf16_f32 v48, v42, v43
	v_cvt_pk_bf16_f32 v49, v44, v45
	v_cvt_pk_bf16_f32 v38, v38, v39
	v_cvt_pk_bf16_f32 v39, v40, v41
	v_cvt_pk_bf16_f32 v40, v34, v35
	v_cvt_pk_bf16_f32 v41, v36, v37
	s_mov_b32 s44, 0x48000
	v_lshl_add_u64 v[158:159], v[136:137], 0, s[44:45]
	global_store_dwordx4 v[158:159], v[46:49], off
	global_store_dwordx4 v[158:159], v[38:41], off offset:256
	v_add_f32_e32 v42, v236, v237
	s_waitcnt vmcnt(28)
	v_pk_add_f32 v[30:31], v[30:31], v[208:209]
	v_pk_add_f32 v[32:33], v[32:33], v[210:211]
	v_pk_add_f32 v[26:27], v[26:27], v[212:213]
	v_pk_add_f32 v[28:29], v[28:29], v[214:215]
	v_pk_add_f32 v[22:23], v[22:23], v[216:217]
	v_pk_add_f32 v[24:25], v[24:25], v[218:219]
	v_pk_add_f32 v[18:19], v[18:19], v[220:221]
	v_pk_add_f32 v[20:21], v[20:21], v[222:223]
	s_mov_b32 s44, 0xa0000
	v_lshl_add_u64 v[156:157], v[134:135], 0, s[44:45]
	global_store_dwordx4 v[156:157], v[30:33], off
	global_store_dwordx4 v[156:157], v[26:29], off offset:16
	global_store_dwordx4 v[156:157], v[22:25], off offset:512
	global_store_dwordx4 v[156:157], v[18:21], off offset:528
	v_pk_mul_f32 v[236:237], v[30:31], v[30:31]
	v_pk_fma_f32 v[236:237], v[32:33], v[32:33], v[236:237]
	v_pk_fma_f32 v[236:237], v[26:27], v[26:27], v[236:237]
	v_pk_fma_f32 v[236:237], v[28:29], v[28:29], v[236:237]
	v_pk_fma_f32 v[236:237], v[22:23], v[22:23], v[236:237]
	v_pk_fma_f32 v[236:237], v[24:25], v[24:25], v[236:237]
	v_pk_fma_f32 v[236:237], v[18:19], v[18:19], v[236:237]
	v_pk_fma_f32 v[236:237], v[20:21], v[20:21], v[236:237]
	v_cvt_pk_bf16_f32 v30, v30, v31
	v_cvt_pk_bf16_f32 v31, v32, v33
	v_cvt_pk_bf16_f32 v32, v26, v27
	v_cvt_pk_bf16_f32 v33, v28, v29
	v_cvt_pk_bf16_f32 v22, v22, v23
	v_cvt_pk_bf16_f32 v23, v24, v25
	v_cvt_pk_bf16_f32 v24, v18, v19
	v_cvt_pk_bf16_f32 v25, v20, v21
	s_mov_b32 s44, 0x50000
	v_lshl_add_u64 v[158:159], v[136:137], 0, s[44:45]
	global_store_dwordx4 v[158:159], v[30:33], off
	global_store_dwordx4 v[158:159], v[22:25], off offset:256
	v_add_f32_e32 v26, v236, v237
	s_waitcnt vmcnt(24)
	v_pk_add_f32 v[14:15], v[14:15], v[224:225]
	v_pk_add_f32 v[16:17], v[16:17], v[226:227]
	v_pk_add_f32 v[10:11], v[10:11], v[228:229]
	v_pk_add_f32 v[12:13], v[12:13], v[230:231]
	v_pk_add_f32 v[6:7], v[6:7], v[232:233]
	v_pk_add_f32 v[8:9], v[8:9], v[234:235]
	v_pk_add_f32 v[2:3], v[2:3], v[130:131]
	v_pk_add_f32 v[4:5], v[4:5], v[132:133]
	s_mov_b32 s44, 0xb0000
	v_lshl_add_u64 v[156:157], v[134:135], 0, s[44:45]
	global_store_dwordx4 v[156:157], v[14:17], off
	global_store_dwordx4 v[156:157], v[10:13], off offset:16
	global_store_dwordx4 v[156:157], v[6:9], off offset:512
	global_store_dwordx4 v[156:157], v[2:5], off offset:528
	v_pk_mul_f32 v[236:237], v[14:15], v[14:15]
	v_pk_fma_f32 v[236:237], v[16:17], v[16:17], v[236:237]
	v_pk_fma_f32 v[236:237], v[10:11], v[10:11], v[236:237]
	v_pk_fma_f32 v[236:237], v[12:13], v[12:13], v[236:237]
	v_pk_fma_f32 v[236:237], v[6:7], v[6:7], v[236:237]
	v_pk_fma_f32 v[236:237], v[8:9], v[8:9], v[236:237]
	v_pk_fma_f32 v[236:237], v[2:3], v[2:3], v[236:237]
	v_pk_fma_f32 v[236:237], v[4:5], v[4:5], v[236:237]
	v_cvt_pk_bf16_f32 v14, v14, v15
	v_cvt_pk_bf16_f32 v15, v16, v17
	v_cvt_pk_bf16_f32 v16, v10, v11
	v_cvt_pk_bf16_f32 v17, v12, v13
	v_cvt_pk_bf16_f32 v6, v6, v7
	v_cvt_pk_bf16_f32 v7, v8, v9
	v_cvt_pk_bf16_f32 v8, v2, v3
	v_cvt_pk_bf16_f32 v9, v4, v5
	s_mov_b32 s44, 0x58000
	v_lshl_add_u64 v[158:159], v[136:137], 0, s[44:45]
	global_store_dwordx4 v[158:159], v[14:17], off
	global_store_dwordx4 v[158:159], v[6:9], off offset:256
	v_add_f32_e32 v10, v236, v237
	v_xor_b32_e32 v236, 16, v175
	v_xor_b32_e32 v237, 32, v175
	v_lshlrev_b32_e32 v236, 2, v236
	v_lshlrev_b32_e32 v237, 2, v237
	ds_bpermute_b32 v123, v236, v122
	ds_bpermute_b32 v107, v236, v106
	ds_bpermute_b32 v91, v236, v90
	ds_bpermute_b32 v75, v236, v74
	ds_bpermute_b32 v59, v236, v58
	ds_bpermute_b32 v43, v236, v42
	ds_bpermute_b32 v27, v236, v26
	ds_bpermute_b32 v11, v236, v10
	s_waitcnt lgkmcnt(0)
	v_add_f32_e32 v122, v122, v123
	v_add_f32_e32 v106, v106, v107
	v_add_f32_e32 v90, v90, v91
	v_add_f32_e32 v74, v74, v75
	v_add_f32_e32 v58, v58, v59
	v_add_f32_e32 v42, v42, v43
	v_add_f32_e32 v26, v26, v27
	v_add_f32_e32 v10, v10, v11
	ds_bpermute_b32 v123, v237, v122
	ds_bpermute_b32 v107, v237, v106
	ds_bpermute_b32 v91, v237, v90
	ds_bpermute_b32 v75, v237, v74
	ds_bpermute_b32 v59, v237, v58
	ds_bpermute_b32 v43, v237, v42
	ds_bpermute_b32 v27, v237, v26
	ds_bpermute_b32 v11, v237, v10
	s_waitcnt lgkmcnt(0)
	v_add_f32_e32 v122, v122, v123
	v_add_f32_e32 v106, v106, v107
	v_add_f32_e32 v90, v90, v91
	v_add_f32_e32 v74, v74, v75
	v_add_f32_e32 v58, v58, v59
	v_add_f32_e32 v42, v42, v43
	v_add_f32_e32 v26, v26, v27
	v_add_f32_e32 v10, v10, v11
	s_mov_b32 s44, 0x2000
	v_lshl_add_u64 v[156:157], v[138:139], 0, s[44:45]
	s_and_saveexec_b64 s[44:45], s[4:5]
	global_store_dword v[138:139], v122, off
	global_store_dword v[138:139], v106, off offset:1024
	global_store_dword v[138:139], v90, off offset:2048
	global_store_dword v[138:139], v74, off offset:3072
	global_store_dword v[156:157], v58, off
	global_store_dword v[156:157], v42, off offset:1024
	global_store_dword v[156:157], v26, off offset:2048
	global_store_dword v[156:157], v10, off offset:3072
	s_or_b64 exec, exec, s[44:45]
	s_andn2_b64 vcc, exec, s[6:7]
	s_mov_b64 s[6:7], -1
	s_cbranch_vccnz .LBB0_3123
	s_andn2_b64 vcc, exec, s[16:17]
	s_cbranch_vccnz .LBB0_3122
	s_barrier
	s_branch .LBB0_3122
